# P1: ~4 us s_sleep before the sample-row task (XCD-class shifts 0/5/8/13 us of the GEMM unit boundaries), on top of v73
# speedup vs baseline: 1.0142x; 1.0142x over previous
; template <int RT, class F>
; __device__ __forceinline__ void sample_gemm_task(const bf16* A, const bf16* Bt, int K, int ct, int row0, int lane, F f) {
;     const int l15 = lane & 15, q4 = lane >> 4;
;     f32x4 acc[RT];
; #pragma unroll
;     for (int rt = 0; rt < RT; ++rt) acc[rt] = (f32x4){0.f, 0.f, 0.f, 0.f};
;     const bf16* bp = Bt + (size_t)(16 * ct + l15) * K + 8 * q4;
;     const bf16* ap = A + (size_t)(row0 + l15) * K + 8 * q4;
; __global__ void __launch_bounds__(NWAVES * 64, 2) fwd_kernel(Params P) {
;     ...
;                 const int mask = (st == 0) ? cls : 3 - cls;
;                 if (mask & 1) for (int tl = (int)blockIdx.x * NWAVES + wave; tl < M / 16; tl += G * NWAVES) gate_tile(P, tl, lane);
;                 if (mask & 2) for (int ct = blockIdx.x; ct < 256; ct += G)
;                     sample_gemm_task<2>((const bf16*)(ws + WS_XN) + (size_t)MP * 1024, (const bf16*)(ws + WS_WIN), 1024, ct, 32 * wave, lane, SEpiProj{(bf16*)(ws + WS_QKVA), (bf16*)(ws + WS_QKVB), (bf16*)(ws + WS_Z)});
.LBB0_176:
	s_bitcmp0_b32 s30, 1
	v_readlane_b32 s4, v247, 33
	s_cselect_b64 s[0:1], -1, 0
	v_readlane_b32 s5, v247, 34
	s_or_b64 s[0:1], s[0:1], s[4:5]
	s_and_b64 vcc, exec, s[0:1]
	s_cbranch_vccnz .LBB0_237
	s_sleep 127
	s_lshl_b32 s2, s31, 5
	v_lshrrev_b32_e32 v2, 2, v11
	v_and_or_b32 v2, v2, 12, s2
	v_ashrrev_i32_e32 v3, 31, v2
	s_mov_b64 s[0:1], 0x10000
	v_lshl_add_u64 v[4:5], v[2:3], 0, s[0:1]
	s_movk_i32 s4, 0xc00
	v_mad_i64_i32 v[12:13], s[0:1], v4, s4, 0
	v_lshlrev_b64 v[6:7], 11, v[2:3]
	s_mov_b64 s[0:1], 0x8000800
	s_waitcnt vmcnt(0)
	v_lshl_add_u64 v[14:15], v[6:7], 0, s[0:1]
	s_mov_b64 s[0:1], 0x8001000
	v_lshl_add_u64 v[18:19], v[6:7], 0, s[0:1]
	v_mad_i64_i32 v[20:21], s[0:1], v4, s4, v[134:135]
	s_mov_b64 s[0:1], 0x8001800
	v_lshlrev_b64 v[10:11], 11, v[4:5]
	v_lshl_add_u64 v[22:23], v[6:7], 0, s[0:1]
	v_mad_i64_i32 v[24:25], s[0:1], v4, s4, v[136:137]
	v_add_u32_e32 v4, 0x10010, v2
	v_ashrrev_i32_e32 v5, 31, v4
	v_lshlrev_b64 v[26:27], 11, v[4:5]
	v_mad_i64_i32 v[28:29], s[0:1], v4, s4, 0
	v_add_u32_e32 v4, 0x10011, v2
	v_ashrrev_i32_e32 v5, 31, v4
	v_lshlrev_b64 v[30:31], 11, v[4:5]
	v_mad_i64_i32 v[32:33], s[0:1], v4, s4, 0
	v_add_u32_e32 v4, 0x10012, v2
	v_add_u32_e32 v2, 0x10013, v2
	v_and_b32_e32 v54, 15, v42
	v_ashrrev_i32_e32 v3, 31, v2
	v_lshlrev_b64 v[38:39], 11, v[2:3]
	v_mad_i64_i32 v[40:41], s[0:1], v2, s4, 0
	v_or_b32_e32 v2, s2, v54
	v_mad_i64_i32 v[36:37], s[0:1], v4, s4, 0
	v_ashrrev_i32_e32 v3, 31, v2
	v_and_b32_e32 v130, 48, v42
	v_readlane_b32 s0, v247, 0
	v_lshlrev_b64 v[2:3], 11, v[2:3]
	v_ashrrev_i32_e32 v5, 31, v4
	v_readlane_b32 s1, v247, 1
	v_readlane_b32 s4, v247, 47
	v_or_b32_e32 v2, v2, v130
	v_or_b32_e32 v16, 0xc00, v12
	v_mov_b32_e32 v17, v13
	v_lshlrev_b64 v[34:35], 11, v[4:5]
	v_lshl_add_u64 v[42:43], s[0:1], 0, v[130:131]
	v_add_u32_e32 v44, s4, v54
	v_lshl_add_u64 v[46:47], s[0:1], 0, v[2:3]
	s_mov_b32 s2, s96
	s_branch .LBB0_179
